# v70 + P kept in accumulator order (8 permlane32_swap per step removed), V tiles staged in natural key order
# speedup vs baseline: 1.0141x; 1.0013x over previous
; __device__ __forceinline__ int v_st(int k, int c) { const int kk = (k & ~0xC) | ((k & 4) << 1) | ((k & 8) >> 1); return ((kk >> 3) * 4 + (c >> 5)) * 512 + ((kk & 7) * 32 + (c & 31)) * 2; }
; __device__ __forceinline__ void attn_unit_pp(int b, int h, int qb, int par, const bf16_t* __restrict__ QBp, const bf16_t* __restrict__ KBp, const bf16_t* __restrict__ VBp, ...
;     ...
;   for (int i = 0; i < 4; ++i) { const int row = sr + 16 * i; woff[i] = g ? (int)(2 * SHM_V) + KSWZ(row, sc * 2) : v_st(row, sc); }
.LBB0_341:
	v_lshrrev_b32_e32 v9, 4, v4
	v_and_b32_e32 v9, 8, v9
	v_lshrrev_b32_e32 v11, 4, v4
	v_bfe_u32 v12, v8, 5, 2
	v_bfe_u32 v8, v4, 4, 2
	v_and_or_b32 v8, v11, 4, v8
	v_and_b32_e32 v11, 48, v2
	v_lshrrev_b32_e32 v9, 1, v9
	v_lshl_or_b32 v8, v8, 6, v11
	s_andn2_b64 vcc, exec, s[0:1]
	v_or_b32_e32 v9, v9, v12
	s_cbranch_vccnz .LBB0_343
	v_lshl_or_b32 v17, v9, 9, v8

; __device__ __forceinline__ bool softmax_pp(f32x16& p0, f32x16& p1, float& m_reg, float& l_reg, f32x16& negm, float& alpha, float& m_run, float dq, float nslope,
;                                            bf16x8& pa0, bf16x8& pa1, bf16x8& pa2, bf16x8& pa3) {
;     ...
;   for (int r = 0; r < 16; ++r) { p0[r] = __builtin_amdgcn_exp2f(p0[r]); p1[r] = __builtin_amdgcn_exp2f(p1[r]); }
;   float ps = 0;
; #pragma unroll
;   for (int r = 0; r < 16; ++r) ps += p0[r];
; #pragma unroll
;   for (int r = 0; r < 16; ++r) ps += p1[r];
;   { auto rr = __builtin_amdgcn_permlane32_swap(__float_as_uint(ps), __float_as_uint(ps), false, false);
;     ps = __uint_as_float(rr[0]) + __uint_as_float(rr[1]); }
;   l_reg = l_reg * alpha + ps;
;     ...
;   PK4(p0, 0, pa0); PK4(p0, 8, pa1); PK4(p1, 0, pa2); PK4(p1, 8, pa3);
.LBB0_369:
	v_max_f32_e32 v172, v172, v15
	v_exp_f32_e32 v2, v98
	v_exp_f32_e32 v3, v99
	v_exp_f32_e32 v4, v100
	v_exp_f32_e32 v5, v101
	v_exp_f32_e32 v12, v116
	v_exp_f32_e32 v6, v102
	v_exp_f32_e32 v7, v103
	v_add_f32_e32 v116, v3, v2
	v_exp_f32_e32 v8, v104
	v_add_f32_e32 v116, v4, v116
	v_exp_f32_e32 v9, v105
	v_add_f32_e32 v116, v5, v116
	v_exp_f32_e32 v100, v106
	v_add_f32_e32 v116, v6, v116
	v_exp_f32_e32 v102, v107
	v_add_f32_e32 v116, v7, v116
	v_exp_f32_e32 v104, v108
	v_add_f32_e32 v116, v8, v116
	v_exp_f32_e32 v106, v109
	v_add_f32_e32 v116, v9, v116
	v_exp_f32_e32 v108, v110
	v_add_f32_e32 v116, v100, v116
	v_exp_f32_e32 v110, v111
	v_add_f32_e32 v116, v102, v116
	v_exp_f32_e32 v112, v112
	v_add_f32_e32 v116, v104, v116
	v_exp_f32_e32 v113, v113
	v_add_f32_e32 v116, v106, v116
	v_exp_f32_e32 v10, v114
	v_add_f32_e32 v116, v108, v116
	v_exp_f32_e32 v11, v115
	v_add_f32_e32 v116, v110, v116
	v_add_f32_e32 v116, v112, v116
	v_exp_f32_e32 v13, v117
	v_add_f32_e32 v116, v113, v116
	v_exp_f32_e32 v14, v118
	v_add_f32_e32 v116, v10, v116
	v_exp_f32_e32 v15, v119
	v_add_f32_e32 v116, v11, v116
	v_exp_f32_e32 v98, v120
	v_add_f32_e32 v116, v12, v116
	v_exp_f32_e32 v99, v121
	v_add_f32_e32 v116, v13, v116
	v_exp_f32_e32 v101, v122
	v_add_f32_e32 v116, v14, v116
	v_exp_f32_e32 v103, v123
	v_add_f32_e32 v116, v15, v116
	v_exp_f32_e32 v105, v124
	v_add_f32_e32 v116, v98, v116
	v_exp_f32_e32 v107, v125
	v_add_f32_e32 v116, v99, v116
	v_exp_f32_e32 v109, v126
	v_add_f32_e32 v116, v101, v116
	v_exp_f32_e32 v111, v127
	v_add_f32_e32 v116, v103, v116
	v_exp_f32_e32 v114, v128
	v_add_f32_e32 v116, v105, v116
	v_exp_f32_e32 v115, v129
	v_add_f32_e32 v116, v107, v116
	v_add_f32_e32 v116, v109, v116
	v_add_f32_e32 v116, v111, v116
	v_add_f32_e32 v116, v114, v116
	v_add_f32_e32 v116, v115, v116
	v_mov_b32_e32 v117, v116
	s_nop 1
	v_permlane32_swap_b32_e32 v116, v117
	v_add_f32_e32 v116, v116, v117
	v_cvt_pk_bf16_f32 v2, v2, v3
	v_cvt_pk_bf16_f32 v3, v4, v5
	v_cvt_pk_bf16_f32 v4, v6, v7
	v_cvt_pk_bf16_f32 v5, v8, v9
	v_cvt_pk_bf16_f32 v6, v100, v102
	v_cvt_pk_bf16_f32 v7, v104, v106
	v_cvt_pk_bf16_f32 v8, v108, v110
	v_cvt_pk_bf16_f32 v9, v112, v113
	v_cvt_pk_bf16_f32 v10, v10, v11
	v_cvt_pk_bf16_f32 v11, v12, v13
	v_cvt_pk_bf16_f32 v12, v14, v15
	v_cvt_pk_bf16_f32 v13, v98, v99
	v_cvt_pk_bf16_f32 v162, v101, v103
	v_cvt_pk_bf16_f32 v163, v105, v107
	v_cvt_pk_bf16_f32 v164, v109, v111
	v_cvt_pk_bf16_f32 v165, v114, v115
	v_fma_f32 v80, v80, v0, v116
	s_branch .LBB0_371

; __device__ __forceinline__ bool softmax_pp(f32x16& p0, f32x16& p1, float& m_reg, float& l_reg, f32x16& negm, float& alpha, float& m_run, float dq, float nslope,
;                                            bf16x8& pa0, bf16x8& pa1, bf16x8& pa2, bf16x8& pa3) {
;     ...
;   for (int r = 0; r < 16; ++r) { p0[r] = __builtin_amdgcn_exp2f(p0[r]); p1[r] = __builtin_amdgcn_exp2f(p1[r]); }
;   float ps = 0;
; #pragma unroll
;   for (int r = 0; r < 16; ++r) ps += p0[r];
; #pragma unroll
;   for (int r = 0; r < 16; ++r) ps += p1[r];
;   { auto rr = __builtin_amdgcn_permlane32_swap(__float_as_uint(ps), __float_as_uint(ps), false, false);
;     ps = __uint_as_float(rr[0]) + __uint_as_float(rr[1]); }
;   l_reg = l_reg * alpha + ps;
;     ...
;   PK4(p0, 0, pa0); PK4(p0, 8, pa1); PK4(p1, 0, pa2); PK4(p1, 8, pa3);
.LBB0_384:
	v_max_f32_e32 v172, v172, v15
	v_exp_f32_e32 v2, v98
	v_exp_f32_e32 v3, v99
	v_exp_f32_e32 v4, v100
	v_exp_f32_e32 v5, v101
	v_exp_f32_e32 v12, v116
	v_exp_f32_e32 v6, v102
	v_exp_f32_e32 v7, v103
	v_add_f32_e32 v116, v3, v2
	v_exp_f32_e32 v8, v104
	v_add_f32_e32 v116, v4, v116
	v_exp_f32_e32 v9, v105
	v_add_f32_e32 v116, v5, v116
	v_exp_f32_e32 v100, v106
	v_add_f32_e32 v116, v6, v116
	v_exp_f32_e32 v102, v107
	v_add_f32_e32 v116, v7, v116
	v_exp_f32_e32 v104, v108
	v_add_f32_e32 v116, v8, v116
	v_exp_f32_e32 v106, v109
	v_add_f32_e32 v116, v9, v116
	v_exp_f32_e32 v108, v110
	v_add_f32_e32 v116, v100, v116
	v_exp_f32_e32 v110, v111
	v_add_f32_e32 v116, v102, v116
	v_exp_f32_e32 v112, v112
	v_add_f32_e32 v116, v104, v116
	v_exp_f32_e32 v113, v113
	v_add_f32_e32 v116, v106, v116
	v_exp_f32_e32 v10, v114
	v_add_f32_e32 v116, v108, v116
	v_exp_f32_e32 v11, v115
	v_add_f32_e32 v116, v110, v116
	v_add_f32_e32 v116, v112, v116
	v_exp_f32_e32 v13, v117
	v_add_f32_e32 v116, v113, v116
	v_exp_f32_e32 v14, v118
	v_add_f32_e32 v116, v10, v116
	v_exp_f32_e32 v15, v119
	v_add_f32_e32 v116, v11, v116
	v_exp_f32_e32 v98, v120
	v_add_f32_e32 v116, v12, v116
	v_exp_f32_e32 v99, v121
	v_add_f32_e32 v116, v13, v116
	v_exp_f32_e32 v101, v122
	v_add_f32_e32 v116, v14, v116
	v_exp_f32_e32 v103, v123
	v_add_f32_e32 v116, v15, v116
	v_exp_f32_e32 v105, v124
	v_add_f32_e32 v116, v98, v116
	v_exp_f32_e32 v107, v125
	v_add_f32_e32 v116, v99, v116
	v_exp_f32_e32 v109, v126
	v_add_f32_e32 v116, v101, v116
	v_exp_f32_e32 v111, v127
	v_add_f32_e32 v116, v103, v116
	v_exp_f32_e32 v114, v128
	v_add_f32_e32 v116, v105, v116
	v_exp_f32_e32 v115, v129
	v_add_f32_e32 v116, v107, v116
	v_add_f32_e32 v116, v109, v116
	v_add_f32_e32 v116, v111, v116
	v_add_f32_e32 v116, v114, v116
	v_add_f32_e32 v116, v115, v116
	v_mov_b32_e32 v117, v116
	s_nop 1
	v_permlane32_swap_b32_e32 v116, v117
	v_add_f32_e32 v116, v116, v117
	v_cvt_pk_bf16_f32 v2, v2, v3
	v_cvt_pk_bf16_f32 v3, v4, v5
	v_cvt_pk_bf16_f32 v4, v6, v7
	v_cvt_pk_bf16_f32 v5, v8, v9
	v_cvt_pk_bf16_f32 v6, v100, v102
	v_cvt_pk_bf16_f32 v7, v104, v106
	v_cvt_pk_bf16_f32 v8, v108, v110
	v_cvt_pk_bf16_f32 v9, v112, v113
	v_cvt_pk_bf16_f32 v10, v10, v11
	v_cvt_pk_bf16_f32 v11, v12, v13
	v_cvt_pk_bf16_f32 v12, v14, v15
	v_cvt_pk_bf16_f32 v13, v98, v99
	v_cvt_pk_bf16_f32 v162, v101, v103
	v_cvt_pk_bf16_f32 v163, v105, v107
	v_cvt_pk_bf16_f32 v164, v109, v111
	v_cvt_pk_bf16_f32 v165, v114, v115
	v_fma_f32 v80, v80, v0, v116
